# diff attention tile B: shorter wave-uniform rescale test on the common path
# baseline (speedup 1.0000x reference)
; template <bool HAS_QK, bool HAS_PV> ...
;     ...
;         const float rm = rowmax32(s0, s1);
;         need = first || __any(rm > 8.f);
;         if (need) { const float dl = first ? rm : fmaxf(rm, 0.f); mrun += dl; f = first ? 1.f : __builtin_amdgcn_exp2f(-dl);
; #pragma unroll
;             for (int r = 0; r < 16; ++r) { s0[r] -= dl; s1[r] -= dl; } }
.LBB0_222:
	v_max_f32_e32 v2, v112, v113
	v_max_f32_e32 v3, v114, v115
	v_max3_f32 v2, v2, v116, v117
	v_max3_f32 v3, v3, v118, v119
	v_max3_f32 v2, v2, v120, v121
	v_max3_f32 v3, v3, v122, v123
	v_max3_f32 v2, v2, v124, v125
	v_max3_f32 v3, v3, v126, v127
	s_nop 3
	v_max3_f32 v2, v2, v96, v97
	v_max3_f32 v3, v3, v98, v99
	v_max3_f32 v2, v2, v100, v101
	v_max3_f32 v3, v3, v102, v103
	v_max3_f32 v2, v2, v104, v105
	v_max3_f32 v3, v3, v106, v107
	v_max3_f32 v2, v2, v108, v109
	v_max3_f32 v3, v3, v110, v111
	v_max_f32_e32 v2, v2, v3
	v_cmp_lt_f32_e32 vcc, s86, v2
	s_cbranch_vccz .LBB0_224
	s_mov_b64 s[4:5], -1
	v_mov_b32_e32 v3, v2
	s_nop 1
	v_permlane32_swap_b32_e32 v2, v3
	v_max_f32_e32 v2, v2, v3
	v_max_f32_e32 v2, v2, v2
	v_max_f32_e32 v2, 0, v2
	v_exp_f32_e64 v14, -v2
	v_add_f32_e32 v15, v15, v2
	v_pk_add_f32 v[112:113], v[112:113], v[2:3] op_sel_hi:[1,0] neg_lo:[0,1] neg_hi:[0,1]
	v_pk_add_f32 v[96:97], v[96:97], v[2:3] op_sel_hi:[1,0] neg_lo:[0,1] neg_hi:[0,1]
	v_pk_add_f32 v[114:115], v[114:115], v[2:3] op_sel_hi:[1,0] neg_lo:[0,1] neg_hi:[0,1]
	v_pk_add_f32 v[98:99], v[98:99], v[2:3] op_sel_hi:[1,0] neg_lo:[0,1] neg_hi:[0,1]
	v_pk_add_f32 v[116:117], v[116:117], v[2:3] op_sel_hi:[1,0] neg_lo:[0,1] neg_hi:[0,1]
	v_pk_add_f32 v[100:101], v[100:101], v[2:3] op_sel_hi:[1,0] neg_lo:[0,1] neg_hi:[0,1]
	v_pk_add_f32 v[118:119], v[118:119], v[2:3] op_sel_hi:[1,0] neg_lo:[0,1] neg_hi:[0,1]
	v_pk_add_f32 v[102:103], v[102:103], v[2:3] op_sel_hi:[1,0] neg_lo:[0,1] neg_hi:[0,1]
	v_pk_add_f32 v[120:121], v[120:121], v[2:3] op_sel_hi:[1,0] neg_lo:[0,1] neg_hi:[0,1]
	v_pk_add_f32 v[104:105], v[104:105], v[2:3] op_sel_hi:[1,0] neg_lo:[0,1] neg_hi:[0,1]
	v_pk_add_f32 v[122:123], v[122:123], v[2:3] op_sel_hi:[1,0] neg_lo:[0,1] neg_hi:[0,1]
	v_pk_add_f32 v[106:107], v[106:107], v[2:3] op_sel_hi:[1,0] neg_lo:[0,1] neg_hi:[0,1]
	v_pk_add_f32 v[124:125], v[124:125], v[2:3] op_sel_hi:[1,0] neg_lo:[0,1] neg_hi:[0,1]
	v_pk_add_f32 v[108:109], v[108:109], v[2:3] op_sel_hi:[1,0] neg_lo:[0,1] neg_hi:[0,1]
	v_pk_add_f32 v[126:127], v[126:127], v[2:3] op_sel_hi:[1,0] neg_lo:[0,1] neg_hi:[0,1]
	v_pk_add_f32 v[110:111], v[110:111], v[2:3] op_sel_hi:[1,0] neg_lo:[0,1] neg_hi:[0,1]
	s_branch .LBB0_225
.LBB0_224:
	s_mov_b64 s[4:5], 0
	v_mov_b32_e32 v14, 1.0
